# P0b parameter vectors fetched once per workgroup (LDS share behind the barrier; the modulation half depends on P0a so it cannot move in front of it); on top of v151
# speedup vs baseline: 1.0030x; 1.0002x over previous
; __global__ void __launch_bounds__(NTHREADS) fwd_megakernel(Args a) {
;     ...
;     { const float* mdl = mods + ((bx & 7) >> 2) * NMOD;
;       const PVec gs = pmul1p(load_pvec(a.f1_pre, lane), load_pvec(mdl + 1 * DM, lane)), sh = load_pvec(mdl + 0 * DM, lane);
;       for (int row = xrow0; row < xrow1; row += 256) {
;         f32x4 h[4], o[4]; load_row_f32(a.x + (size_t)row * DM, lane, h);
;         norm_mod_r(h, o, gs, sh);
.LBB0_173:
	s_or_b64 exec, exec, s[0:1]
	s_waitcnt lgkmcnt(0)
	s_barrier
	s_and_b32 s0, s20, 7
	v_writelane_b32 v238, s0, 25
	s_lshl_b32 s1, s0, 11
	s_and_b32 s0, s20, -8
	v_writelane_b32 v238, s0, 26
	s_add_i32 s0, s1, s0
	s_add_i32 s22, s0, s21
	s_bfe_u32 s0, s20, 0x10002
	s_add_i32 s96, s1, 0x800
	s_mul_i32 s0, s0, 0x9000
	s_add_u32 s0, s12, s0
	v_writelane_b32 v238, s1, 27
	s_addc_u32 s1, s13, 0
	v_writelane_b32 v238, s0, 28
	s_cmp_lt_i32 s22, s96
	v_lshlrev_b32_e32 v38, 2, v161
	v_writelane_b32 v238, s1, 29
	v_mov_b32_e32 v163, 0
	v_lshlrev_b32_e32 v162, 4, v161
	s_cselect_b64 s[0:1], -1, 0
	v_lshl_add_u64 v[16:17], s[48:49], 0, v[162:163]
	v_writelane_b32 v238, s0, 30
	s_cmp_ge_i32 s22, s96
	v_lshlrev_b32_e32 v164, 2, v38
	v_mbcnt_lo_u32_b32 v174, -1, 0
	v_writelane_b32 v238, s1, 31
	s_cbranch_scc1 .LBB0_186
	v_readlane_b32 s8, v238, 28
	v_mov_b32_e32 v165, v163
	v_readlane_b32 s9, v238, 29
	s_mov_b64 s[0:1], 0x1000
	v_mbcnt_hi_u32_b32 v20, -1, v174
	v_lshl_add_u64 v[0:1], s[8:9], 0, v[164:165]
	v_lshl_add_u64 v[2:3], v[0:1], 0, s[0:1]
	v_readlane_b32 s98, v238, 40
	s_nop 3
	s_cmp_lg_u32 s98, 0
	s_cbranch_scc1 .Lpv_p0b_0
	global_load_dwordx4 v[176:179], v[2:3], off offset:1024

; __global__ void __launch_bounds__(NTHREADS) fwd_megakernel(Args a) {
;     ...
;     { const float* mdl = mods + ((bx & 7) >> 2) * NMOD;
;       const PVec gs = pmul1p(load_pvec(a.f1_pre, lane), load_pvec(mdl + 1 * DM, lane)), sh = load_pvec(mdl + 0 * DM, lane);
;       for (int row = xrow0; row < xrow1; row += 256) {
;         f32x4 h[4], o[4]; load_row_f32(a.x + (size_t)row * DM, lane, h);
;         norm_mod_r(h, o, gs, sh);
;         store_row_bf16(R1 + (size_t)row * DM, lane, o);
;       }
.Lpv_p0b_1:
	v_add_co_u32_e32 v0, vcc, 0x1000, v0
	v_and_b32_e32 v21, 64, v20
	s_nop 0
	v_addc_co_u32_e32 v1, vcc, 0, v1, vcc
	s_cmp_lg_u32 s98, 2
	s_cbranch_scc1 .Lpv_p0b_2
	global_load_dwordx4 v[176:179], v[0:1], off
.Lpv_p0b_2:
	s_cmp_lg_u32 s98, 3
	s_cbranch_scc1 .Lpv_p0b_3
	global_load_dwordx4 v[176:179], v[16:17], off offset:1024
.Lpv_p0b_3:
	s_cmp_lg_u32 s98, 4
	s_cbranch_scc1 .Lpv_p0b_4
	global_load_dwordx4 v[176:179], v[16:17], off offset:2048
.Lpv_p0b_4:
	s_cmp_lg_u32 s98, 5
	s_cbranch_scc1 .Lpv_p0b_5
	global_load_dwordx4 v[176:179], v[2:3], off offset:3072
.Lpv_p0b_5:
	s_cmp_lg_u32 s98, 6
	s_cbranch_scc1 .Lpv_p0b_6
	global_load_dwordx4 v[176:179], v[16:17], off
.Lpv_p0b_6:
	s_cmp_lg_u32 s98, 7
	s_cbranch_scc1 .Lpv_p0b_7
	global_load_dwordx4 v[176:179], v[16:17], off offset:3072
.Lpv_p0b_7:
	s_nop 0
	s_cmp_lg_u32 s98, 0
	s_cbranch_scc1 .Lpv_p0b_8
	global_load_dwordx4 v[180:183], v164, s[8:9]
.Lpv_p0b_8:
	s_cmp_lg_u32 s98, 1
	s_cbranch_scc1 .Lpv_p0b_9
	global_load_dwordx4 v[180:183], v164, s[8:9] offset:1024
.Lpv_p0b_9:
	s_cmp_lg_u32 s98, 2
	s_cbranch_scc1 .Lpv_p0b_10
	global_load_dwordx4 v[180:183], v164, s[8:9] offset:2048
.Lpv_p0b_10:
	s_cmp_lg_u32 s98, 3
	s_cbranch_scc1 .Lpv_p0b_11
	global_load_dwordx4 v[180:183], v164, s[8:9] offset:3072
.Lpv_p0b_11:
	s_lshl_b32 s98, s98, 10
	s_nop 0
	v_add_u32_e32 v192, s98, v164
	s_waitcnt vmcnt(0)
	ds_write_b128 v192, v[176:179]
	ds_write_b128 v192, v[180:183] offset:8192
	ds_write_b128 v192, v[184:187] offset:16384
	ds_write_b128 v192, v[188:191] offset:24576
	s_waitcnt lgkmcnt(0)
	s_barrier
	ds_read_b128 v[22:25], v164
	ds_read_b128 v[26:29], v164 offset:1024
	ds_read_b128 v[30:33], v164 offset:2048
	ds_read_b128 v[34:37], v164 offset:3072
	ds_read_b128 v[48:51], v164 offset:4096
	ds_read_b128 v[52:55], v164 offset:5120
	ds_read_b128 v[56:59], v164 offset:6144
	ds_read_b128 v[60:63], v164 offset:7168
	ds_read_b128 v[0:3], v164 offset:8192
	ds_read_b128 v[4:7], v164 offset:9216
	ds_read_b128 v[8:11], v164 offset:10240
	ds_read_b128 v[12:15], v164 offset:11264
	s_waitcnt lgkmcnt(0)
	v_xor_b32_e32 v41, 1, v20
	v_add_u32_e32 v21, 64, v21
	v_xor_b32_e32 v42, 2, v20
	v_cmp_lt_i32_e32 vcc, v41, v21
	s_ashr_i32 s23, s22, 31
	v_xor_b32_e32 v43, 4, v20
	v_cndmask_b32_e32 v41, v20, v41, vcc
	v_cmp_lt_i32_e32 vcc, v42, v21
	v_xor_b32_e32 v44, 8, v20
	s_lshl_b64 s[12:13], s[22:23], 11
	v_cndmask_b32_e32 v42, v20, v42, vcc
	v_cmp_lt_i32_e32 vcc, v43, v21
	v_xor_b32_e32 v45, 16, v20
	s_add_u32 s12, s30, s12
	v_cndmask_b32_e32 v43, v20, v43, vcc
	v_cmp_lt_i32_e32 vcc, v44, v21
	v_lshlrev_b32_e32 v18, 3, v161
	v_mov_b32_e32 v19, v163
	v_xor_b32_e32 v46, 32, v20
	v_cndmask_b32_e32 v44, v20, v44, vcc
	v_cmp_lt_i32_e32 vcc, v45, v21
	s_addc_u32 s13, s31, s13
	s_lshl_b64 s[14:15], s[22:23], 12
	v_cndmask_b32_e32 v45, v20, v45, vcc
	v_cmp_lt_i32_e32 vcc, v46, v21
	v_lshl_add_u64 v[18:19], s[12:13], 0, v[18:19]
	s_add_u32 s12, s36, s14
	v_cndmask_b32_e32 v20, v20, v46, vcc
	s_addc_u32 s13, s37, s15
	s_mov_b64 s[0:1], 0x5a00600
	s_mov_b64 s[8:9], 0x800
	v_lshlrev_b32_e32 v46, 2, v20
	v_lshl_add_u64 v[20:21], s[12:13], 0, v[162:163]
	v_mov_b32_e32 v39, 0x358637bd
	s_mov_b32 s3, 0xf800000
	v_mov_b32_e32 v40, 0x260
	v_lshlrev_b32_e32 v41, 2, v41
	v_lshlrev_b32_e32 v42, 2, v42
	v_lshlrev_b32_e32 v43, 2, v43
	v_lshlrev_b32_e32 v44, 2, v44
	v_lshlrev_b32_e32 v45, 2, v45
	v_lshl_add_u64 v[18:19], v[18:19], 0, s[0:1]
	v_lshl_add_u64 v[20:21], v[20:21], 0, s[8:9]
	s_mov_b64 s[8:9], 0x80000
	s_mov_b64 s[12:13], 0x100000
	s_mov_b32 s11, s22
	s_waitcnt vmcnt(9)
	v_pk_add_f32 v[32:33], v[32:33], 1.0 op_sel_hi:[1,0]
	v_pk_add_f32 v[68:69], v[30:31], 1.0 op_sel_hi:[1,0]
	v_pk_add_f32 v[24:25], v[24:25], 1.0 op_sel_hi:[1,0]
	v_pk_add_f32 v[64:65], v[22:23], 1.0 op_sel_hi:[1,0]
	v_pk_add_f32 v[28:29], v[28:29], 1.0 op_sel_hi:[1,0]
	v_pk_add_f32 v[66:67], v[26:27], 1.0 op_sel_hi:[1,0]
	s_waitcnt vmcnt(8)
	v_pk_mul_f32 v[22:23], v[36:37], v[24:25]
	v_pk_mul_f32 v[24:25], v[34:35], v[64:65]
	s_waitcnt vmcnt(6)
	v_pk_add_f32 v[34:35], v[54:55], 1.0 op_sel_hi:[1,0]
	v_pk_add_f32 v[36:37], v[52:53], 1.0 op_sel_hi:[1,0]
	v_pk_mul_f32 v[26:27], v[50:51], v[28:29]
	v_pk_mul_f32 v[28:29], v[48:49], v[66:67]
	s_waitcnt vmcnt(5)
	v_pk_mul_f32 v[30:31], v[58:59], v[32:33]
	v_pk_mul_f32 v[32:33], v[56:57], v[68:69]
	s_waitcnt vmcnt(4)
	v_pk_mul_f32 v[34:35], v[62:63], v[34:35]
	v_pk_mul_f32 v[36:37], v[60:61], v[36:37]
